# merge GEMMs B and C: the previous merge GEMM's epilogue stores retire before the main loop starts
# speedup vs baseline: 1.0030x; 1.0030x over previous
.LBB0_1425:
	s_add_u32 s44, s20, 0x100
	v_mov_b32_e32 v2, 0
	s_addc_u32 s45, s21, 0
	s_mov_b32 s46, -2
	v_mov_b32_e32 v3, v2
	v_mov_b32_e32 v4, v2
	v_mov_b32_e32 v5, v2
	v_mov_b32_e32 v6, v2
	v_mov_b32_e32 v7, v2
	v_mov_b32_e32 v8, v2
	v_mov_b32_e32 v9, v2
	v_mov_b32_e32 v18, v2
	v_mov_b32_e32 v19, v2
	v_mov_b32_e32 v20, v2
	v_mov_b32_e32 v21, v2
	v_mov_b32_e32 v22, v2
	v_mov_b32_e32 v23, v2
	v_mov_b32_e32 v24, v2
	v_mov_b32_e32 v25, v2
	v_mov_b32_e32 v34, v2
	v_mov_b32_e32 v35, v2
	v_mov_b32_e32 v36, v2
	v_mov_b32_e32 v37, v2
	v_mov_b32_e32 v38, v2
	v_mov_b32_e32 v39, v2
	v_mov_b32_e32 v40, v2
	v_mov_b32_e32 v41, v2
	v_mov_b32_e32 v50, v2
	v_mov_b32_e32 v51, v2
	v_mov_b32_e32 v52, v2
	v_mov_b32_e32 v53, v2
	v_mov_b32_e32 v54, v2
	v_mov_b32_e32 v55, v2
	v_mov_b32_e32 v56, v2
	v_mov_b32_e32 v57, v2
	v_mov_b32_e32 v10, v2
	v_mov_b32_e32 v11, v2
	v_mov_b32_e32 v12, v2
	v_mov_b32_e32 v13, v2
	v_mov_b32_e32 v14, v2
	v_mov_b32_e32 v15, v2
	v_mov_b32_e32 v16, v2
	v_mov_b32_e32 v17, v2
	v_mov_b32_e32 v26, v2
	v_mov_b32_e32 v27, v2
	v_mov_b32_e32 v28, v2
	v_mov_b32_e32 v29, v2
	v_mov_b32_e32 v30, v2
	v_mov_b32_e32 v31, v2
	v_mov_b32_e32 v32, v2
	v_mov_b32_e32 v33, v2
	v_mov_b32_e32 v42, v2
	v_mov_b32_e32 v43, v2
	v_mov_b32_e32 v44, v2
	v_mov_b32_e32 v45, v2
	v_mov_b32_e32 v46, v2
	v_mov_b32_e32 v47, v2
	v_mov_b32_e32 v48, v2
	v_mov_b32_e32 v49, v2
	v_mov_b32_e32 v58, v2
	v_mov_b32_e32 v59, v2
	v_mov_b32_e32 v60, v2
	v_mov_b32_e32 v61, v2
	v_mov_b32_e32 v62, v2
	v_mov_b32_e32 v63, v2
	v_mov_b32_e32 v64, v2
	v_mov_b32_e32 v65, v2
	v_mov_b32_e32 v66, v2
	v_mov_b32_e32 v67, v2
	v_mov_b32_e32 v68, v2
	v_mov_b32_e32 v69, v2
	v_mov_b32_e32 v70, v2
	v_mov_b32_e32 v71, v2
	v_mov_b32_e32 v72, v2
	v_mov_b32_e32 v73, v2
	v_mov_b32_e32 v82, v2
	v_mov_b32_e32 v83, v2
	v_mov_b32_e32 v84, v2
	v_mov_b32_e32 v85, v2
	v_mov_b32_e32 v86, v2
	v_mov_b32_e32 v87, v2
	v_mov_b32_e32 v88, v2
	v_mov_b32_e32 v89, v2
	v_mov_b32_e32 v98, v2
	v_mov_b32_e32 v99, v2
	v_mov_b32_e32 v100, v2
	v_mov_b32_e32 v101, v2
	v_mov_b32_e32 v102, v2
	v_mov_b32_e32 v103, v2
	v_mov_b32_e32 v104, v2
	v_mov_b32_e32 v105, v2
	v_mov_b32_e32 v114, v2
	v_mov_b32_e32 v115, v2
	v_mov_b32_e32 v116, v2
	v_mov_b32_e32 v117, v2
	v_mov_b32_e32 v118, v2
	v_mov_b32_e32 v119, v2
	v_mov_b32_e32 v120, v2
	v_mov_b32_e32 v121, v2
	v_mov_b32_e32 v74, v2
	v_mov_b32_e32 v75, v2
	v_mov_b32_e32 v76, v2
	v_mov_b32_e32 v77, v2
	v_mov_b32_e32 v78, v2
	v_mov_b32_e32 v79, v2
	v_mov_b32_e32 v80, v2
	v_mov_b32_e32 v81, v2
	v_mov_b32_e32 v90, v2
	v_mov_b32_e32 v91, v2
	v_mov_b32_e32 v92, v2
	v_mov_b32_e32 v93, v2
	v_mov_b32_e32 v94, v2
	v_mov_b32_e32 v95, v2
	v_mov_b32_e32 v96, v2
	v_mov_b32_e32 v97, v2
	v_mov_b32_e32 v106, v2
	v_mov_b32_e32 v107, v2
	v_mov_b32_e32 v108, v2
	v_mov_b32_e32 v109, v2
	v_mov_b32_e32 v110, v2
	v_mov_b32_e32 v111, v2
	v_mov_b32_e32 v112, v2
	v_mov_b32_e32 v113, v2
	v_mov_b32_e32 v122, v2
	v_mov_b32_e32 v123, v2
	v_mov_b32_e32 v124, v2
	v_mov_b32_e32 v125, v2
	v_mov_b32_e32 v126, v2
	v_mov_b32_e32 v127, v2
	v_mov_b32_e32 v128, v2
	v_mov_b32_e32 v129, v2
	s_waitcnt vmcnt(0)

.LBB0_1445:
	s_ashr_i32 s17, s16, 31
	s_lshl_b64 s[18:19], s[16:17], 17
	s_add_u32 s18, s42, s18
	s_addc_u32 s19, s43, s19
	s_and_b64 s[20:21], s[8:9], exec
	s_cselect_b32 s17, s19, s25
	s_cselect_b32 s56, s18, s24
	s_ashr_i32 s15, s14, 31
	s_lshl_b64 s[20:21], s[14:15], 17
	s_add_u32 s20, s44, s20
	s_addc_u32 s21, s45, s21
	s_and_b64 s[26:27], s[8:9], exec
	v_mov_b32_e32 v2, 0
	s_cselect_b32 s15, s21, s23
	s_cselect_b32 s57, s20, s22
	s_mov_b32 s30, 0
	s_mov_b64 s[26:27], -1
	s_mov_b64 s[28:29], 0
	v_mov_b32_e32 v3, v2
	v_mov_b32_e32 v4, v2
	v_mov_b32_e32 v5, v2
	v_mov_b32_e32 v6, v2
	v_mov_b32_e32 v7, v2
	v_mov_b32_e32 v8, v2
	v_mov_b32_e32 v9, v2
	v_mov_b32_e32 v18, v2
	v_mov_b32_e32 v19, v2
	v_mov_b32_e32 v20, v2
	v_mov_b32_e32 v21, v2
	v_mov_b32_e32 v22, v2
	v_mov_b32_e32 v23, v2
	v_mov_b32_e32 v24, v2
	v_mov_b32_e32 v25, v2
	v_mov_b32_e32 v34, v2
	v_mov_b32_e32 v35, v2
	v_mov_b32_e32 v36, v2
	v_mov_b32_e32 v37, v2
	v_mov_b32_e32 v38, v2
	v_mov_b32_e32 v39, v2
	v_mov_b32_e32 v40, v2
	v_mov_b32_e32 v41, v2
	v_mov_b32_e32 v50, v2
	v_mov_b32_e32 v51, v2
	v_mov_b32_e32 v52, v2
	v_mov_b32_e32 v53, v2
	v_mov_b32_e32 v54, v2
	v_mov_b32_e32 v55, v2
	v_mov_b32_e32 v56, v2
	v_mov_b32_e32 v57, v2
	v_mov_b32_e32 v10, v2
	v_mov_b32_e32 v11, v2
	v_mov_b32_e32 v12, v2
	v_mov_b32_e32 v13, v2
	v_mov_b32_e32 v14, v2
	v_mov_b32_e32 v15, v2
	v_mov_b32_e32 v16, v2
	v_mov_b32_e32 v17, v2
	v_mov_b32_e32 v26, v2
	v_mov_b32_e32 v27, v2
	v_mov_b32_e32 v28, v2
	v_mov_b32_e32 v29, v2
	v_mov_b32_e32 v30, v2
	v_mov_b32_e32 v31, v2
	v_mov_b32_e32 v32, v2
	v_mov_b32_e32 v33, v2
	v_mov_b32_e32 v42, v2
	v_mov_b32_e32 v43, v2
	v_mov_b32_e32 v44, v2
	v_mov_b32_e32 v45, v2
	v_mov_b32_e32 v46, v2
	v_mov_b32_e32 v47, v2
	v_mov_b32_e32 v48, v2
	v_mov_b32_e32 v49, v2
	v_mov_b32_e32 v58, v2
	v_mov_b32_e32 v59, v2
	v_mov_b32_e32 v60, v2
	v_mov_b32_e32 v61, v2
	v_mov_b32_e32 v62, v2
	v_mov_b32_e32 v63, v2
	v_mov_b32_e32 v64, v2
	v_mov_b32_e32 v65, v2
	v_mov_b32_e32 v66, v2
	v_mov_b32_e32 v67, v2
	v_mov_b32_e32 v68, v2
	v_mov_b32_e32 v69, v2
	v_mov_b32_e32 v70, v2
	v_mov_b32_e32 v71, v2
	v_mov_b32_e32 v72, v2
	v_mov_b32_e32 v73, v2
	v_mov_b32_e32 v82, v2
	v_mov_b32_e32 v83, v2
	v_mov_b32_e32 v84, v2
	v_mov_b32_e32 v85, v2
	v_mov_b32_e32 v86, v2
	v_mov_b32_e32 v87, v2
	v_mov_b32_e32 v88, v2
	v_mov_b32_e32 v89, v2
	v_mov_b32_e32 v98, v2
	v_mov_b32_e32 v99, v2
	v_mov_b32_e32 v100, v2
	v_mov_b32_e32 v101, v2
	v_mov_b32_e32 v102, v2
	v_mov_b32_e32 v103, v2
	v_mov_b32_e32 v104, v2
	v_mov_b32_e32 v105, v2
	v_mov_b32_e32 v114, v2
	v_mov_b32_e32 v115, v2
	v_mov_b32_e32 v116, v2
	v_mov_b32_e32 v117, v2
	v_mov_b32_e32 v118, v2
	v_mov_b32_e32 v119, v2
	v_mov_b32_e32 v120, v2
	v_mov_b32_e32 v121, v2
	v_mov_b32_e32 v74, v2
	v_mov_b32_e32 v75, v2
	v_mov_b32_e32 v76, v2
	v_mov_b32_e32 v77, v2
	v_mov_b32_e32 v78, v2
	v_mov_b32_e32 v79, v2
	v_mov_b32_e32 v80, v2
	v_mov_b32_e32 v81, v2
	v_mov_b32_e32 v90, v2
	v_mov_b32_e32 v91, v2
	v_mov_b32_e32 v92, v2
	v_mov_b32_e32 v93, v2
	v_mov_b32_e32 v94, v2
	v_mov_b32_e32 v95, v2
	v_mov_b32_e32 v96, v2
	v_mov_b32_e32 v97, v2
	v_mov_b32_e32 v106, v2
	v_mov_b32_e32 v107, v2
	v_mov_b32_e32 v108, v2
	v_mov_b32_e32 v109, v2
	v_mov_b32_e32 v110, v2
	v_mov_b32_e32 v111, v2
	v_mov_b32_e32 v112, v2
	v_mov_b32_e32 v113, v2
	v_mov_b32_e32 v122, v2
	v_mov_b32_e32 v123, v2
	v_mov_b32_e32 v124, v2
	v_mov_b32_e32 v125, v2
	v_mov_b32_e32 v126, v2
	v_mov_b32_e32 v127, v2
	v_mov_b32_e32 v128, v2
	v_mov_b32_e32 v129, v2
	s_waitcnt vmcnt(0)
